# UQ GEMM RoPE epilogue stores widened too: v_permlane16_swap pairs + dwordx4 (16 instead of 32 stores per thread per tile)
# baseline (speedup 1.0000x reference)
; __device__ __forceinline__ unsigned cvt_pk_bf16(float lo, float hi) { unsigned r; asm volatile("v_cvt_pk_bf16_f32 %0, %1, %2" : "=v"(r) : "v"(lo), "v"(hi)); return r; }
;     __device__ __forceinline__ void operator()(const f32x4 (&acc)[2][2][4][2], const Unit& u, int wr, int wc, int fr_in, int fq_in) const {
;     ...
;         for (int bj = 0; bj < 2; ++bj) {
;             const int cg0 = u.pn * BM + bj * HALF + wc * 32;
;             if (cg0 >= 384) continue;
;             const bool isrope = ((cg0 >> 5) % 3) == 2;
; #pragma unroll
;             for (int ai = 0; ai < 2; ++ai)
; #pragma unroll
;                 for (int m = 0; m < 4; ++m) {
;                     const int r = row0 + ai * HALF + m * 16;
;                     f32x4 x1 = acc[ai][bj][m][0] * qs, x2 = acc[ai][bj][m][1] * qs;
;                     if (isrope) {
;                         const int s = r % LP;
;                         const f32x4 cs = *(const f32x4*)(rope + (size_t)s * 32 + 4 * fq), sn = *(const f32x4*)(rope + (size_t)s * 32 + 16 + 4 * fq);
;                         const f32x4 o1 = x1 * cs - x2 * sn, o2 = x2 * cs + x1 * sn; x1 = o1; x2 = o2;
;                     }
;                     bf16_t* p = U + (size_t)r * DIN + 2048 + cg0 + 4 * fq;
;                     u32x2 w1, w2; w1.x = cvt_pk_bf16(x1[0], x1[1]); w1.y = cvt_pk_bf16(x1[2], x1[3]); w2.x = cvt_pk_bf16(x2[0], x2[1]); w2.y = cvt_pk_bf16(x2[2], x2[3]);
;                     *(u32x2*)p = w1; *(u32x2*)(p + 16) = w2;
;                 }
.LBB0_726:
	v_and_b32_e32 v168, 16, v252
	v_lshrrev_b32_e32 v169, 1, v168
	v_add_u32_e32 v168, v168, v169
	v_mov_b32_e32 v169, 0
	s_ashr_i32 s6, s36, 5
	s_mul_hi_i32 s7, s6, 0x55555556
	s_lshr_b32 s37, s7, 31
	s_add_i32 s7, s7, s37
	s_mul_i32 s7, s7, 3
	s_sub_i32 s6, s6, s7
	s_cmp_eq_u32 s6, 2
	s_cselect_b64 s[38:39], -1, 0
	s_cmp_lg_u32 s6, 2
	s_cbranch_scc1 .LBB0_728
	v_mul_hi_i32 v0, v74, s33
	v_lshrrev_b32_e32 v76, 31, v0
	v_ashrrev_i32_e32 v0, 12, v0
	v_add_u32_e32 v0, v0, v76
	v_mul_i32_i24_e32 v0, 0x2080, v0
	v_sub_u32_e32 v76, v74, v0
	v_ashrrev_i32_e32 v77, 31, v76
	v_lshlrev_b64 v[76:77], 7, v[76:77]
	v_lshl_add_u64 v[76:77], s[24:25], 0, v[76:77]
	v_lshlrev_b32_e32 v0, 2, v75
	v_lshl_add_u64 v[80:81], v[76:77], 0, v[0:1]
	flat_load_dwordx4 v[76:79], v[80:81] offset:64
	flat_load_dwordx4 v[90:93], v[80:81]
	s_waitcnt vmcnt(0) lgkmcnt(0)
	v_pk_mul_f32 v[80:81], v[144:145], v[78:79]
	v_pk_mul_f32 v[94:95], v[142:143], v[76:77]
	v_pk_mul_f32 v[78:79], v[148:149], v[78:79]
	v_pk_mul_f32 v[76:77], v[146:147], v[76:77]
	v_pk_fma_f32 v[148:149], v[148:149], v[92:93], v[80:81] neg_lo:[0,0,1] neg_hi:[0,0,1]
	v_pk_fma_f32 v[146:147], v[146:147], v[90:91], v[94:95] neg_lo:[0,0,1] neg_hi:[0,0,1]
	v_pk_fma_f32 v[144:145], v[144:145], v[92:93], v[78:79]
	v_pk_fma_f32 v[142:143], v[142:143], v[90:91], v[76:77]
.LBB0_728:
	v_mov_b64_e32 v[76:77], s[16:17]
	s_ashr_i32 s37, s36, 31
	v_mad_i64_i32 v[76:77], s[6:7], v74, s45, v[76:77]
	v_lshl_add_u64 v[76:77], s[36:37], 1, v[76:77]
	v_lshlrev_b32_e32 v0, 1, v75
	v_lshl_add_u64 v[76:77], v[76:77], 0, v[0:1]
	v_lshl_add_u64 v[78:79], v[76:77], 0, s[84:85]
	v_add_co_u32_e32 v76, vcc, 0x1000, v76
	v_cvt_pk_bf16_f32 v160, v146, v147
	v_cvt_pk_bf16_f32 v161, v148, v149
	v_cvt_pk_bf16_f32 v162, v142, v143
	v_cvt_pk_bf16_f32 v163, v144, v145
	s_nop 1
	v_addc_co_u32_e32 v77, vcc, 0, v77, vcc
	v_lshl_add_u64 v[170:171], v[76:77], 0, v[168:169]
	s_nop 1
	v_permlane16_swap_b32_e32 v160, v162
	v_permlane16_swap_b32_e32 v161, v163
	flat_store_dwordx4 v[170:171], v[160:163]
	v_cndmask_b32_e64 v76, 0, 1, s[38:39]
	v_cmp_ne_u32_e64 s[6:7], 1, v76
	s_andn2_b64 vcc, exec, s[38:39]
	v_or_b32_e32 v76, 16, v74
	s_cbranch_vccnz .LBB0_730
	v_mul_hi_i32 v77, v76, s33
	v_lshrrev_b32_e32 v78, 31, v77
	v_ashrrev_i32_e32 v77, 12, v77
	v_add_u32_e32 v77, v77, v78
	v_mul_i32_i24_e32 v77, 0x2080, v77
	v_sub_u32_e32 v78, v76, v77
	v_ashrrev_i32_e32 v79, 31, v78
	v_lshlrev_b64 v[78:79], 7, v[78:79]
	v_lshl_add_u64 v[78:79], s[24:25], 0, v[78:79]
	v_lshlrev_b32_e32 v80, 2, v75
	v_mov_b32_e32 v81, v1
	v_lshl_add_u64 v[90:91], v[78:79], 0, v[80:81]
	flat_load_dwordx4 v[78:81], v[90:91] offset:64
	s_nop 0
	flat_load_dwordx4 v[90:93], v[90:91]
	s_waitcnt vmcnt(0) lgkmcnt(0)
	v_pk_mul_f32 v[94:95], v[136:137], v[80:81]
	v_pk_mul_f32 v[96:97], v[134:135], v[78:79]
	v_pk_mul_f32 v[80:81], v[140:141], v[80:81]
	v_pk_mul_f32 v[78:79], v[138:139], v[78:79]
	v_pk_fma_f32 v[140:141], v[140:141], v[92:93], v[94:95] neg_lo:[0,0,1] neg_hi:[0,0,1]
	v_pk_fma_f32 v[138:139], v[138:139], v[90:91], v[96:97] neg_lo:[0,0,1] neg_hi:[0,0,1]
	v_pk_fma_f32 v[136:137], v[136:137], v[92:93], v[80:81]
	v_pk_fma_f32 v[134:135], v[134:135], v[90:91], v[78:79]
.LBB0_730:
	v_mov_b64_e32 v[78:79], s[16:17]
	v_mad_i64_i32 v[76:77], s[38:39], v76, s45, v[78:79]
	v_lshl_add_u64 v[76:77], s[36:37], 1, v[76:77]
	v_lshl_add_u64 v[76:77], v[76:77], 0, v[0:1]
	v_lshl_add_u64 v[78:79], v[76:77], 0, s[84:85]
	v_add_co_u32_e32 v76, vcc, 0x1000, v76
	v_cvt_pk_bf16_f32 v164, v138, v139
	v_cvt_pk_bf16_f32 v165, v140, v141
	v_cvt_pk_bf16_f32 v166, v134, v135
	v_cvt_pk_bf16_f32 v167, v136, v137
	s_nop 1
	v_addc_co_u32_e32 v77, vcc, 0, v77, vcc
	v_lshl_add_u64 v[170:171], v[76:77], 0, v[168:169]
	s_nop 1
	v_permlane16_swap_b32_e32 v164, v166
	v_permlane16_swap_b32_e32 v165, v167
	flat_store_dwordx4 v[170:171], v[164:167]
	s_and_b64 vcc, exec, s[6:7]
	v_or_b32_e32 v76, 32, v74
	s_cbranch_vccnz .LBB0_732
	v_mul_hi_i32 v77, v76, s33
	v_lshrrev_b32_e32 v78, 31, v77
	v_ashrrev_i32_e32 v77, 12, v77
	v_add_u32_e32 v77, v77, v78
	v_mul_i32_i24_e32 v77, 0x2080, v77
	v_sub_u32_e32 v78, v76, v77
	v_ashrrev_i32_e32 v79, 31, v78
	v_lshlrev_b64 v[78:79], 7, v[78:79]
	v_lshl_add_u64 v[78:79], s[24:25], 0, v[78:79]
	v_lshlrev_b32_e32 v80, 2, v75
	v_mov_b32_e32 v81, v1
	v_lshl_add_u64 v[90:91], v[78:79], 0, v[80:81]
	flat_load_dwordx4 v[78:81], v[90:91] offset:64
	s_nop 0
	flat_load_dwordx4 v[90:93], v[90:91]
	s_waitcnt vmcnt(0) lgkmcnt(0)
	v_pk_mul_f32 v[94:95], v[128:129], v[80:81]
	v_pk_mul_f32 v[96:97], v[126:127], v[78:79]
	v_pk_mul_f32 v[80:81], v[132:133], v[80:81]
	v_pk_mul_f32 v[78:79], v[130:131], v[78:79]
	v_pk_fma_f32 v[132:133], v[132:133], v[92:93], v[94:95] neg_lo:[0,0,1] neg_hi:[0,0,1]
	v_pk_fma_f32 v[130:131], v[130:131], v[90:91], v[96:97] neg_lo:[0,0,1] neg_hi:[0,0,1]
	v_pk_fma_f32 v[128:129], v[128:129], v[92:93], v[80:81]
	v_pk_fma_f32 v[126:127], v[126:127], v[90:91], v[78:79]
; __device__ __forceinline__ unsigned cvt_pk_bf16(float lo, float hi) { unsigned r; asm volatile("v_cvt_pk_bf16_f32 %0, %1, %2" : "=v"(r) : "v"(lo), "v"(hi)); return r; }
;     __device__ __forceinline__ void operator()(const f32x4 (&acc)[2][2][4][2], const Unit& u, int wr, int wc, int fr_in, int fq_in) const {
;     ...
;         for (int bj = 0; bj < 2; ++bj) {
;             const int cg0 = u.pn * BM + bj * HALF + wc * 32;
;             if (cg0 >= 384) continue;
;             const bool isrope = ((cg0 >> 5) % 3) == 2;
; #pragma unroll
;             for (int ai = 0; ai < 2; ++ai)
; #pragma unroll
;                 for (int m = 0; m < 4; ++m) {
;                     const int r = row0 + ai * HALF + m * 16;
;                     f32x4 x1 = acc[ai][bj][m][0] * qs, x2 = acc[ai][bj][m][1] * qs;
;                     if (isrope) {
;                         const int s = r % LP;
;                         const f32x4 cs = *(const f32x4*)(rope + (size_t)s * 32 + 4 * fq), sn = *(const f32x4*)(rope + (size_t)s * 32 + 16 + 4 * fq);
;                         const f32x4 o1 = x1 * cs - x2 * sn, o2 = x2 * cs + x1 * sn; x1 = o1; x2 = o2;
;                     }
;                     bf16_t* p = U + (size_t)r * DIN + 2048 + cg0 + 4 * fq;
;                     u32x2 w1, w2; w1.x = cvt_pk_bf16(x1[0], x1[1]); w1.y = cvt_pk_bf16(x1[2], x1[3]); w2.x = cvt_pk_bf16(x2[0], x2[1]); w2.y = cvt_pk_bf16(x2[2], x2[3]);
;                     *(u32x2*)p = w1; *(u32x2*)(p + 16) = w2;
;                 }
.LBB0_732:
	v_mov_b64_e32 v[78:79], s[16:17]
	v_mad_i64_i32 v[76:77], s[38:39], v76, s45, v[78:79]
	v_lshl_add_u64 v[76:77], s[36:37], 1, v[76:77]
	v_lshl_add_u64 v[76:77], v[76:77], 0, v[0:1]
	v_lshl_add_u64 v[78:79], v[76:77], 0, s[84:85]
	v_add_co_u32_e32 v76, vcc, 0x1000, v76
	v_cvt_pk_bf16_f32 v160, v130, v131
	v_cvt_pk_bf16_f32 v161, v132, v133
	v_cvt_pk_bf16_f32 v162, v126, v127
	v_cvt_pk_bf16_f32 v163, v128, v129
	s_nop 1
	v_addc_co_u32_e32 v77, vcc, 0, v77, vcc
	v_lshl_add_u64 v[170:171], v[76:77], 0, v[168:169]
	s_nop 1
	v_permlane16_swap_b32_e32 v160, v162
	v_permlane16_swap_b32_e32 v161, v163
	flat_store_dwordx4 v[170:171], v[160:163]
	s_and_b64 vcc, exec, s[6:7]
	v_or_b32_e32 v76, 48, v74
	s_cbranch_vccnz .LBB0_734
	v_mul_hi_i32 v77, v76, s33
	v_lshrrev_b32_e32 v78, 31, v77
	v_ashrrev_i32_e32 v77, 12, v77
	v_add_u32_e32 v77, v77, v78
	v_mul_i32_i24_e32 v77, 0x2080, v77
	v_sub_u32_e32 v78, v76, v77
	v_ashrrev_i32_e32 v79, 31, v78
	v_lshlrev_b64 v[78:79], 7, v[78:79]
	v_lshl_add_u64 v[78:79], s[24:25], 0, v[78:79]
	v_lshlrev_b32_e32 v80, 2, v75
	v_mov_b32_e32 v81, v1
	v_lshl_add_u64 v[90:91], v[78:79], 0, v[80:81]
	flat_load_dwordx4 v[78:81], v[90:91] offset:64
	s_nop 0
	flat_load_dwordx4 v[90:93], v[90:91]
	s_waitcnt vmcnt(0) lgkmcnt(0)
	v_pk_mul_f32 v[94:95], v[120:121], v[80:81]
	v_pk_mul_f32 v[96:97], v[118:119], v[78:79]
	v_pk_mul_f32 v[80:81], v[124:125], v[80:81]
	v_pk_mul_f32 v[78:79], v[122:123], v[78:79]
	v_pk_fma_f32 v[124:125], v[124:125], v[92:93], v[94:95] neg_lo:[0,0,1] neg_hi:[0,0,1]
	v_pk_fma_f32 v[122:123], v[122:123], v[90:91], v[96:97] neg_lo:[0,0,1] neg_hi:[0,0,1]
	v_pk_fma_f32 v[120:121], v[120:121], v[92:93], v[80:81]
	v_pk_fma_f32 v[118:119], v[118:119], v[90:91], v[78:79]
.LBB0_734:
	v_mov_b64_e32 v[78:79], s[16:17]
	v_mad_i64_i32 v[76:77], s[38:39], v76, s45, v[78:79]
	v_lshl_add_u64 v[76:77], s[36:37], 1, v[76:77]
	v_lshl_add_u64 v[76:77], v[76:77], 0, v[0:1]
	v_lshl_add_u64 v[78:79], v[76:77], 0, s[84:85]
	v_add_co_u32_e32 v76, vcc, 0x1000, v76
	v_cvt_pk_bf16_f32 v164, v122, v123
	v_cvt_pk_bf16_f32 v165, v124, v125
	v_cvt_pk_bf16_f32 v166, v118, v119
	v_cvt_pk_bf16_f32 v167, v120, v121
	s_nop 1
	v_addc_co_u32_e32 v77, vcc, 0, v77, vcc
	v_lshl_add_u64 v[170:171], v[76:77], 0, v[168:169]
	s_nop 1
	v_permlane16_swap_b32_e32 v164, v166
	v_permlane16_swap_b32_e32 v165, v167
	flat_store_dwordx4 v[170:171], v[164:167]
	s_and_b64 vcc, exec, s[6:7]
	v_add_u32_e32 v76, 0x80, v74
	s_cbranch_vccnz .LBB0_736
	v_mul_hi_i32 v77, v76, s33
	v_lshrrev_b32_e32 v78, 31, v77
	v_ashrrev_i32_e32 v77, 12, v77
	v_add_u32_e32 v77, v77, v78
	v_mul_i32_i24_e32 v77, 0x2080, v77
	v_sub_u32_e32 v78, v76, v77
	v_ashrrev_i32_e32 v79, 31, v78
	v_lshlrev_b64 v[78:79], 7, v[78:79]
	v_lshl_add_u64 v[78:79], s[24:25], 0, v[78:79]
	v_lshlrev_b32_e32 v80, 2, v75
	v_mov_b32_e32 v81, v1
	v_lshl_add_u64 v[90:91], v[78:79], 0, v[80:81]
	flat_load_dwordx4 v[78:81], v[90:91] offset:64
	s_nop 0
	flat_load_dwordx4 v[90:93], v[90:91]
	s_waitcnt vmcnt(0) lgkmcnt(0)
	v_pk_mul_f32 v[94:95], v[112:113], v[80:81]
	v_pk_mul_f32 v[96:97], v[110:111], v[78:79]
	v_pk_mul_f32 v[80:81], v[116:117], v[80:81]
	v_pk_mul_f32 v[78:79], v[114:115], v[78:79]
	v_pk_fma_f32 v[116:117], v[116:117], v[92:93], v[94:95] neg_lo:[0,0,1] neg_hi:[0,0,1]
	v_pk_fma_f32 v[114:115], v[114:115], v[90:91], v[96:97] neg_lo:[0,0,1] neg_hi:[0,0,1]
	v_pk_fma_f32 v[112:113], v[112:113], v[92:93], v[80:81]
	v_pk_fma_f32 v[110:111], v[110:111], v[90:91], v[78:79]
.LBB0_736:
	v_mov_b64_e32 v[78:79], s[16:17]
	v_mad_i64_i32 v[76:77], s[38:39], v76, s45, v[78:79]
	v_lshl_add_u64 v[76:77], s[36:37], 1, v[76:77]
	v_lshl_add_u64 v[76:77], v[76:77], 0, v[0:1]
	v_lshl_add_u64 v[78:79], v[76:77], 0, s[84:85]
	v_add_co_u32_e32 v76, vcc, 0x1000, v76
	v_cvt_pk_bf16_f32 v160, v114, v115
	v_cvt_pk_bf16_f32 v161, v116, v117
	v_cvt_pk_bf16_f32 v162, v110, v111
	v_cvt_pk_bf16_f32 v163, v112, v113
	s_nop 1
	v_addc_co_u32_e32 v77, vcc, 0, v77, vcc
	v_lshl_add_u64 v[170:171], v[76:77], 0, v[168:169]
	s_nop 1
	v_permlane16_swap_b32_e32 v160, v162
	v_permlane16_swap_b32_e32 v161, v163
	flat_store_dwordx4 v[170:171], v[160:163]
	s_and_b64 vcc, exec, s[6:7]
	v_add_u32_e32 v76, 0x90, v74
	s_cbranch_vccnz .LBB0_738
	v_mul_hi_i32 v77, v76, s33
	v_lshrrev_b32_e32 v78, 31, v77
	v_ashrrev_i32_e32 v77, 12, v77
	v_add_u32_e32 v77, v77, v78
	v_mul_i32_i24_e32 v77, 0x2080, v77
	v_sub_u32_e32 v78, v76, v77
	v_ashrrev_i32_e32 v79, 31, v78
	v_lshlrev_b64 v[78:79], 7, v[78:79]
	v_lshl_add_u64 v[78:79], s[24:25], 0, v[78:79]
	v_lshlrev_b32_e32 v80, 2, v75
	v_mov_b32_e32 v81, v1
	v_lshl_add_u64 v[90:91], v[78:79], 0, v[80:81]
	flat_load_dwordx4 v[78:81], v[90:91] offset:64
	s_nop 0
	flat_load_dwordx4 v[90:93], v[90:91]
	s_waitcnt vmcnt(0) lgkmcnt(0)
	v_pk_mul_f32 v[94:95], v[104:105], v[80:81]
	v_pk_mul_f32 v[96:97], v[102:103], v[78:79]
	v_pk_mul_f32 v[80:81], v[108:109], v[80:81]
	v_pk_mul_f32 v[78:79], v[106:107], v[78:79]
	v_pk_fma_f32 v[108:109], v[108:109], v[92:93], v[94:95] neg_lo:[0,0,1] neg_hi:[0,0,1]
	v_pk_fma_f32 v[106:107], v[106:107], v[90:91], v[96:97] neg_lo:[0,0,1] neg_hi:[0,0,1]
	v_pk_fma_f32 v[104:105], v[104:105], v[92:93], v[80:81]
	v_pk_fma_f32 v[102:103], v[102:103], v[90:91], v[78:79]
; __device__ __forceinline__ unsigned cvt_pk_bf16(float lo, float hi) { unsigned r; asm volatile("v_cvt_pk_bf16_f32 %0, %1, %2" : "=v"(r) : "v"(lo), "v"(hi)); return r; }
;     __device__ __forceinline__ void operator()(const f32x4 (&acc)[2][2][4][2], const Unit& u, int wr, int wc, int fr_in, int fq_in) const {
;     ...
;         for (int bj = 0; bj < 2; ++bj) {
;             const int cg0 = u.pn * BM + bj * HALF + wc * 32;
;             if (cg0 >= 384) continue;
;             const bool isrope = ((cg0 >> 5) % 3) == 2;
; #pragma unroll
;             for (int ai = 0; ai < 2; ++ai)
; #pragma unroll
;                 for (int m = 0; m < 4; ++m) {
;                     const int r = row0 + ai * HALF + m * 16;
;                     f32x4 x1 = acc[ai][bj][m][0] * qs, x2 = acc[ai][bj][m][1] * qs;
;                     if (isrope) {
;                         const int s = r % LP;
;                         const f32x4 cs = *(const f32x4*)(rope + (size_t)s * 32 + 4 * fq), sn = *(const f32x4*)(rope + (size_t)s * 32 + 16 + 4 * fq);
;                         const f32x4 o1 = x1 * cs - x2 * sn, o2 = x2 * cs + x1 * sn; x1 = o1; x2 = o2;
;                     }
;                     bf16_t* p = U + (size_t)r * DIN + 2048 + cg0 + 4 * fq;
;                     u32x2 w1, w2; w1.x = cvt_pk_bf16(x1[0], x1[1]); w1.y = cvt_pk_bf16(x1[2], x1[3]); w2.x = cvt_pk_bf16(x2[0], x2[1]); w2.y = cvt_pk_bf16(x2[2], x2[3]);
;                     *(u32x2*)p = w1; *(u32x2*)(p + 16) = w2;
;                 }
.LBB0_738:
	v_mov_b64_e32 v[78:79], s[16:17]
	v_mad_i64_i32 v[76:77], s[38:39], v76, s45, v[78:79]
	v_lshl_add_u64 v[76:77], s[36:37], 1, v[76:77]
	v_lshl_add_u64 v[76:77], v[76:77], 0, v[0:1]
	v_lshl_add_u64 v[78:79], v[76:77], 0, s[84:85]
	v_add_co_u32_e32 v76, vcc, 0x1000, v76
	v_cvt_pk_bf16_f32 v164, v106, v107
	v_cvt_pk_bf16_f32 v165, v108, v109
	v_cvt_pk_bf16_f32 v166, v102, v103
	v_cvt_pk_bf16_f32 v167, v104, v105
	s_nop 1
	v_addc_co_u32_e32 v77, vcc, 0, v77, vcc
	v_lshl_add_u64 v[170:171], v[76:77], 0, v[168:169]
	s_nop 1
	v_permlane16_swap_b32_e32 v164, v166
	v_permlane16_swap_b32_e32 v165, v167
	flat_store_dwordx4 v[170:171], v[164:167]
	s_and_b64 vcc, exec, s[6:7]
	v_add_u32_e32 v76, 0xa0, v74
	s_cbranch_vccnz .LBB0_740
	v_mul_hi_i32 v77, v76, s33
	v_lshrrev_b32_e32 v78, 31, v77
	v_ashrrev_i32_e32 v77, 12, v77
	v_add_u32_e32 v77, v77, v78
	v_mul_i32_i24_e32 v77, 0x2080, v77
	v_sub_u32_e32 v78, v76, v77
	v_ashrrev_i32_e32 v79, 31, v78
	v_lshlrev_b64 v[78:79], 7, v[78:79]
	v_lshl_add_u64 v[78:79], s[24:25], 0, v[78:79]
	v_lshlrev_b32_e32 v80, 2, v75
	v_mov_b32_e32 v81, v1
	v_lshl_add_u64 v[90:91], v[78:79], 0, v[80:81]
	flat_load_dwordx4 v[78:81], v[90:91] offset:64
	s_nop 0
	flat_load_dwordx4 v[90:93], v[90:91]
	s_waitcnt vmcnt(0) lgkmcnt(0)
	v_pk_mul_f32 v[94:95], v[84:85], v[80:81]
	v_pk_mul_f32 v[96:97], v[82:83], v[78:79]
	v_pk_mul_f32 v[80:81], v[88:89], v[80:81]
	v_pk_mul_f32 v[78:79], v[86:87], v[78:79]
	v_pk_fma_f32 v[88:89], v[88:89], v[92:93], v[94:95] neg_lo:[0,0,1] neg_hi:[0,0,1]
	v_pk_fma_f32 v[86:87], v[86:87], v[90:91], v[96:97] neg_lo:[0,0,1] neg_hi:[0,0,1]
	v_pk_fma_f32 v[84:85], v[84:85], v[92:93], v[80:81]
	v_pk_fma_f32 v[82:83], v[82:83], v[90:91], v[78:79]
.LBB0_740:
	v_mov_b64_e32 v[78:79], s[16:17]
	v_mad_i64_i32 v[76:77], s[38:39], v76, s45, v[78:79]
	v_lshl_add_u64 v[76:77], s[36:37], 1, v[76:77]
	v_lshl_add_u64 v[76:77], v[76:77], 0, v[0:1]
	v_lshl_add_u64 v[78:79], v[76:77], 0, s[84:85]
	v_add_co_u32_e32 v76, vcc, 0x1000, v76
	v_cvt_pk_bf16_f32 v160, v86, v87
	v_cvt_pk_bf16_f32 v161, v88, v89
	v_cvt_pk_bf16_f32 v162, v82, v83
	v_cvt_pk_bf16_f32 v163, v84, v85
	s_nop 1
	v_addc_co_u32_e32 v77, vcc, 0, v77, vcc
	v_lshl_add_u64 v[170:171], v[76:77], 0, v[168:169]
	s_nop 1
	v_permlane16_swap_b32_e32 v160, v162
	v_permlane16_swap_b32_e32 v161, v163
	flat_store_dwordx4 v[170:171], v[160:163]
	s_and_b64 vcc, exec, s[6:7]
	v_add_u32_e32 v76, 0xb0, v74
	s_cbranch_vccnz .LBB0_742
	v_mul_hi_i32 v77, v76, s33
	v_lshrrev_b32_e32 v78, 31, v77
	v_ashrrev_i32_e32 v77, 12, v77
	v_add_u32_e32 v77, v77, v78
	v_mul_i32_i24_e32 v77, 0x2080, v77
	v_sub_u32_e32 v78, v76, v77
	v_ashrrev_i32_e32 v79, 31, v78
	v_lshlrev_b64 v[78:79], 7, v[78:79]
	v_lshl_add_u64 v[78:79], s[24:25], 0, v[78:79]
	v_lshlrev_b32_e32 v80, 2, v75
	v_mov_b32_e32 v81, v1
	v_lshl_add_u64 v[82:83], v[78:79], 0, v[80:81]
	flat_load_dwordx4 v[78:81], v[82:83] offset:64
	s_nop 0
	flat_load_dwordx4 v[82:85], v[82:83]
	s_waitcnt vmcnt(0) lgkmcnt(0)
	v_pk_mul_f32 v[86:87], v[68:69], v[80:81]
	v_pk_mul_f32 v[88:89], v[66:67], v[78:79]
	v_pk_mul_f32 v[80:81], v[72:73], v[80:81]
	v_pk_mul_f32 v[78:79], v[70:71], v[78:79]
	v_pk_fma_f32 v[72:73], v[72:73], v[84:85], v[86:87] neg_lo:[0,0,1] neg_hi:[0,0,1]
	v_pk_fma_f32 v[70:71], v[70:71], v[82:83], v[88:89] neg_lo:[0,0,1] neg_hi:[0,0,1]
	v_pk_fma_f32 v[68:69], v[68:69], v[84:85], v[80:81]
	v_pk_fma_f32 v[66:67], v[66:67], v[82:83], v[78:79]
.LBB0_742:
	v_mov_b64_e32 v[78:79], s[16:17]
	v_mad_i64_i32 v[76:77], s[6:7], v76, s45, v[78:79]
	v_lshl_add_u64 v[76:77], s[36:37], 1, v[76:77]
	v_lshl_add_u64 v[76:77], v[76:77], 0, v[0:1]
	v_cvt_pk_bf16_f32 v164, v70, v71
	v_cvt_pk_bf16_f32 v165, v72, v73
	v_cvt_pk_bf16_f32 v166, v66, v67
	v_cvt_pk_bf16_f32 v167, v68, v69
	v_add_co_u32_e32 v68, vcc, 0x1000, v76
	v_lshl_add_u64 v[78:79], v[76:77], 0, s[84:85]
	s_nop 0
	v_addc_co_u32_e32 v69, vcc, 0, v77, vcc
	v_lshl_add_u64 v[170:171], v[68:69], 0, v[168:169]
	s_nop 1
	v_permlane16_swap_b32_e32 v164, v166
	v_permlane16_swap_b32_e32 v165, v167
	flat_store_dwordx4 v[170:171], v[164:167]
	s_bitset1_b32 s36, 7
	s_cmpk_gt_i32 s36, 0x17f
	s_cbranch_scc1 .LBB0_725
.LBB0_743:
	v_and_b32_e32 v168, 16, v252
	v_lshrrev_b32_e32 v169, 1, v168
	v_add_u32_e32 v168, v168, v169
	v_mov_b32_e32 v169, 0
	s_ashr_i32 s6, s36, 5
	s_mul_hi_i32 s7, s6, 0x55555556
	s_lshr_b32 s37, s7, 31
	s_add_i32 s7, s7, s37
	s_mul_i32 s7, s7, 3
	s_sub_i32 s6, s6, s7
	s_cmp_eq_u32 s6, 2
	s_cselect_b64 s[38:39], -1, 0
	s_cmp_lg_u32 s6, 2
	v_lshlrev_b32_e32 v66, 2, v75
	s_cbranch_scc1 .LBB0_745
	v_mul_hi_i32 v0, v74, s33
	v_lshrrev_b32_e32 v67, 31, v0
	v_ashrrev_i32_e32 v0, 12, v0
	v_add_u32_e32 v0, v0, v67
	v_mul_i32_i24_e32 v0, 0x2080, v0
	v_sub_u32_e32 v68, v74, v0
	v_ashrrev_i32_e32 v69, 31, v68
	v_lshlrev_b64 v[68:69], 7, v[68:69]
	v_lshl_add_u64 v[68:69], s[24:25], 0, v[68:69]
	v_mov_b32_e32 v67, v1
	v_lshl_add_u64 v[72:73], v[68:69], 0, v[66:67]
	flat_load_dwordx4 v[68:71], v[72:73] offset:64
	flat_load_dwordx4 v[76:79], v[72:73]
	s_waitcnt vmcnt(0) lgkmcnt(0)
	v_pk_mul_f32 v[72:73], v[60:61], v[70:71]
	v_pk_mul_f32 v[80:81], v[58:59], v[68:69]
	v_pk_mul_f32 v[70:71], v[64:65], v[70:71]
	v_pk_mul_f32 v[68:69], v[62:63], v[68:69]
	v_pk_fma_f32 v[64:65], v[64:65], v[78:79], v[72:73] neg_lo:[0,0,1] neg_hi:[0,0,1]
	v_pk_fma_f32 v[62:63], v[62:63], v[76:77], v[80:81] neg_lo:[0,0,1] neg_hi:[0,0,1]
	v_pk_fma_f32 v[60:61], v[60:61], v[78:79], v[70:71]
	v_pk_fma_f32 v[58:59], v[58:59], v[76:77], v[68:69]
; __device__ __forceinline__ unsigned cvt_pk_bf16(float lo, float hi) { unsigned r; asm volatile("v_cvt_pk_bf16_f32 %0, %1, %2" : "=v"(r) : "v"(lo), "v"(hi)); return r; }
;     __device__ __forceinline__ void operator()(const f32x4 (&acc)[2][2][4][2], const Unit& u, int wr, int wc, int fr_in, int fq_in) const {
;     ...
;         for (int bj = 0; bj < 2; ++bj) {
;             const int cg0 = u.pn * BM + bj * HALF + wc * 32;
;             if (cg0 >= 384) continue;
;             const bool isrope = ((cg0 >> 5) % 3) == 2;
; #pragma unroll
;             for (int ai = 0; ai < 2; ++ai)
; #pragma unroll
;                 for (int m = 0; m < 4; ++m) {
;                     const int r = row0 + ai * HALF + m * 16;
;                     f32x4 x1 = acc[ai][bj][m][0] * qs, x2 = acc[ai][bj][m][1] * qs;
;                     if (isrope) {
;                         const int s = r % LP;
;                         const f32x4 cs = *(const f32x4*)(rope + (size_t)s * 32 + 4 * fq), sn = *(const f32x4*)(rope + (size_t)s * 32 + 16 + 4 * fq);
;                         const f32x4 o1 = x1 * cs - x2 * sn, o2 = x2 * cs + x1 * sn; x1 = o1; x2 = o2;
;                     }
;                     bf16_t* p = U + (size_t)r * DIN + 2048 + cg0 + 4 * fq;
;                     u32x2 w1, w2; w1.x = cvt_pk_bf16(x1[0], x1[1]); w1.y = cvt_pk_bf16(x1[2], x1[3]); w2.x = cvt_pk_bf16(x2[0], x2[1]); w2.y = cvt_pk_bf16(x2[2], x2[3]);
;                     *(u32x2*)p = w1; *(u32x2*)(p + 16) = w2;
;                 }
.LBB0_745:
	v_mov_b64_e32 v[68:69], s[16:17]
	v_mad_i64_i32 v[68:69], s[6:7], v74, s45, v[68:69]
	v_lshlrev_b32_e32 v0, 1, v75
	s_ashr_i32 s37, s36, 31
	v_lshl_add_u64 v[68:69], v[68:69], 0, v[0:1]
	v_lshl_add_u64 v[68:69], s[36:37], 1, v[68:69]
	v_cvt_pk_bf16_f32 v160, v62, v63
	v_cvt_pk_bf16_f32 v161, v64, v65
	v_cvt_pk_bf16_f32 v162, v58, v59
	v_cvt_pk_bf16_f32 v163, v60, v61
	v_add_co_u32_e32 v60, vcc, 0x1000, v68
	v_lshl_add_u64 v[70:71], v[68:69], 0, s[84:85]
	s_nop 0
	v_addc_co_u32_e32 v61, vcc, 0, v69, vcc
	v_lshl_add_u64 v[170:171], v[60:61], 0, v[168:169]
	s_nop 1
	v_permlane16_swap_b32_e32 v160, v162
	v_permlane16_swap_b32_e32 v161, v163
	flat_store_dwordx4 v[170:171], v[160:163]
	v_cndmask_b32_e64 v58, 0, 1, s[38:39]
	v_cmp_ne_u32_e64 s[6:7], 1, v58
	s_andn2_b64 vcc, exec, s[38:39]
	v_or_b32_e32 v58, 16, v74
	s_cbranch_vccnz .LBB0_747
	v_mul_hi_i32 v59, v58, s33
	v_lshrrev_b32_e32 v60, 31, v59
	v_ashrrev_i32_e32 v59, 12, v59
	v_add_u32_e32 v59, v59, v60
	v_mul_i32_i24_e32 v59, 0x2080, v59
	v_sub_u32_e32 v60, v58, v59
	v_ashrrev_i32_e32 v61, 31, v60
	v_lshlrev_b64 v[60:61], 7, v[60:61]
	v_lshl_add_u64 v[60:61], s[24:25], 0, v[60:61]
	v_mov_b32_e32 v67, v1
	v_lshl_add_u64 v[64:65], v[60:61], 0, v[66:67]
	flat_load_dwordx4 v[60:63], v[64:65] offset:64
	flat_load_dwordx4 v[68:71], v[64:65]
	s_waitcnt vmcnt(0) lgkmcnt(0)
	v_pk_mul_f32 v[64:65], v[52:53], v[62:63]
	v_pk_mul_f32 v[72:73], v[50:51], v[60:61]
	v_pk_mul_f32 v[62:63], v[56:57], v[62:63]
	v_pk_mul_f32 v[60:61], v[54:55], v[60:61]
	v_pk_fma_f32 v[56:57], v[56:57], v[70:71], v[64:65] neg_lo:[0,0,1] neg_hi:[0,0,1]
	v_pk_fma_f32 v[54:55], v[54:55], v[68:69], v[72:73] neg_lo:[0,0,1] neg_hi:[0,0,1]
	v_pk_fma_f32 v[52:53], v[52:53], v[70:71], v[62:63]
	v_pk_fma_f32 v[50:51], v[50:51], v[68:69], v[60:61]
.LBB0_747:
	v_mov_b64_e32 v[60:61], s[16:17]
	v_mad_i64_i32 v[58:59], s[38:39], v58, s45, v[60:61]
	v_lshl_add_u64 v[58:59], v[58:59], 0, v[0:1]
	v_lshl_add_u64 v[58:59], s[36:37], 1, v[58:59]
	v_cvt_pk_bf16_f32 v164, v54, v55
	v_cvt_pk_bf16_f32 v165, v56, v57
	v_cvt_pk_bf16_f32 v166, v50, v51
	v_cvt_pk_bf16_f32 v167, v52, v53
	v_add_co_u32_e32 v52, vcc, 0x1000, v58
	v_lshl_add_u64 v[60:61], v[58:59], 0, s[84:85]
	s_nop 0
	v_addc_co_u32_e32 v53, vcc, 0, v59, vcc
	v_lshl_add_u64 v[170:171], v[52:53], 0, v[168:169]
	s_nop 1
	v_permlane16_swap_b32_e32 v164, v166
	v_permlane16_swap_b32_e32 v165, v167
	flat_store_dwordx4 v[170:171], v[164:167]
	s_and_b64 vcc, exec, s[6:7]
	v_or_b32_e32 v50, 32, v74
	s_cbranch_vccnz .LBB0_749
	v_mul_hi_i32 v51, v50, s33
	v_lshrrev_b32_e32 v52, 31, v51
	v_ashrrev_i32_e32 v51, 12, v51
	v_add_u32_e32 v51, v51, v52
	v_mul_i32_i24_e32 v51, 0x2080, v51
	v_sub_u32_e32 v52, v50, v51
	v_ashrrev_i32_e32 v53, 31, v52
	v_lshlrev_b64 v[52:53], 7, v[52:53]
	v_lshl_add_u64 v[52:53], s[24:25], 0, v[52:53]
	v_mov_b32_e32 v67, v1
	v_lshl_add_u64 v[56:57], v[52:53], 0, v[66:67]
	flat_load_dwordx4 v[52:55], v[56:57] offset:64
	s_nop 0
	flat_load_dwordx4 v[56:59], v[56:57]
	s_waitcnt vmcnt(0) lgkmcnt(0)
	v_pk_mul_f32 v[60:61], v[44:45], v[54:55]
	v_pk_mul_f32 v[62:63], v[42:43], v[52:53]
	v_pk_mul_f32 v[54:55], v[48:49], v[54:55]
	v_pk_mul_f32 v[52:53], v[46:47], v[52:53]
	v_pk_fma_f32 v[48:49], v[48:49], v[58:59], v[60:61] neg_lo:[0,0,1] neg_hi:[0,0,1]
	v_pk_fma_f32 v[46:47], v[46:47], v[56:57], v[62:63] neg_lo:[0,0,1] neg_hi:[0,0,1]
	v_pk_fma_f32 v[44:45], v[44:45], v[58:59], v[54:55]
	v_pk_fma_f32 v[42:43], v[42:43], v[56:57], v[52:53]
.LBB0_749:
	v_mov_b64_e32 v[52:53], s[16:17]
	v_mad_i64_i32 v[50:51], s[38:39], v50, s45, v[52:53]
	v_lshl_add_u64 v[50:51], v[50:51], 0, v[0:1]
	v_lshl_add_u64 v[50:51], s[36:37], 1, v[50:51]
	v_cvt_pk_bf16_f32 v160, v46, v47
	v_cvt_pk_bf16_f32 v161, v48, v49
	v_cvt_pk_bf16_f32 v162, v42, v43
	v_cvt_pk_bf16_f32 v163, v44, v45
	v_add_co_u32_e32 v44, vcc, 0x1000, v50
	v_lshl_add_u64 v[52:53], v[50:51], 0, s[84:85]
	s_nop 0
	v_addc_co_u32_e32 v45, vcc, 0, v51, vcc
	v_lshl_add_u64 v[170:171], v[44:45], 0, v[168:169]
	s_nop 1
	v_permlane16_swap_b32_e32 v160, v162
	v_permlane16_swap_b32_e32 v161, v163
	flat_store_dwordx4 v[170:171], v[160:163]
	s_and_b64 vcc, exec, s[6:7]
	v_or_b32_e32 v42, 48, v74
	s_cbranch_vccnz .LBB0_751
	v_mul_hi_i32 v43, v42, s33
	v_lshrrev_b32_e32 v44, 31, v43
	v_ashrrev_i32_e32 v43, 12, v43
	v_add_u32_e32 v43, v43, v44
	v_mul_i32_i24_e32 v43, 0x2080, v43
	v_sub_u32_e32 v44, v42, v43
	v_ashrrev_i32_e32 v45, 31, v44
	v_lshlrev_b64 v[44:45], 7, v[44:45]
	v_lshl_add_u64 v[44:45], s[24:25], 0, v[44:45]
	v_mov_b32_e32 v67, v1
	v_lshl_add_u64 v[48:49], v[44:45], 0, v[66:67]
	flat_load_dwordx4 v[44:47], v[48:49] offset:64
	s_nop 0
	flat_load_dwordx4 v[48:51], v[48:49]
	s_waitcnt vmcnt(0) lgkmcnt(0)
	v_pk_mul_f32 v[52:53], v[36:37], v[46:47]
	v_pk_mul_f32 v[54:55], v[34:35], v[44:45]
	v_pk_mul_f32 v[46:47], v[40:41], v[46:47]
	v_pk_mul_f32 v[44:45], v[38:39], v[44:45]
	v_pk_fma_f32 v[40:41], v[40:41], v[50:51], v[52:53] neg_lo:[0,0,1] neg_hi:[0,0,1]
	v_pk_fma_f32 v[38:39], v[38:39], v[48:49], v[54:55] neg_lo:[0,0,1] neg_hi:[0,0,1]
	v_pk_fma_f32 v[36:37], v[36:37], v[50:51], v[46:47]
	v_pk_fma_f32 v[34:35], v[34:35], v[48:49], v[44:45]
; __device__ __forceinline__ unsigned cvt_pk_bf16(float lo, float hi) { unsigned r; asm volatile("v_cvt_pk_bf16_f32 %0, %1, %2" : "=v"(r) : "v"(lo), "v"(hi)); return r; }
;     __device__ __forceinline__ void operator()(const f32x4 (&acc)[2][2][4][2], const Unit& u, int wr, int wc, int fr_in, int fq_in) const {
;     ...
;         for (int bj = 0; bj < 2; ++bj) {
;             const int cg0 = u.pn * BM + bj * HALF + wc * 32;
;             if (cg0 >= 384) continue;
;             const bool isrope = ((cg0 >> 5) % 3) == 2;
; #pragma unroll
;             for (int ai = 0; ai < 2; ++ai)
; #pragma unroll
;                 for (int m = 0; m < 4; ++m) {
;                     const int r = row0 + ai * HALF + m * 16;
;                     f32x4 x1 = acc[ai][bj][m][0] * qs, x2 = acc[ai][bj][m][1] * qs;
;                     if (isrope) {
;                         const int s = r % LP;
;                         const f32x4 cs = *(const f32x4*)(rope + (size_t)s * 32 + 4 * fq), sn = *(const f32x4*)(rope + (size_t)s * 32 + 16 + 4 * fq);
;                         const f32x4 o1 = x1 * cs - x2 * sn, o2 = x2 * cs + x1 * sn; x1 = o1; x2 = o2;
;                     }
;                     bf16_t* p = U + (size_t)r * DIN + 2048 + cg0 + 4 * fq;
;                     u32x2 w1, w2; w1.x = cvt_pk_bf16(x1[0], x1[1]); w1.y = cvt_pk_bf16(x1[2], x1[3]); w2.x = cvt_pk_bf16(x2[0], x2[1]); w2.y = cvt_pk_bf16(x2[2], x2[3]);
;                     *(u32x2*)p = w1; *(u32x2*)(p + 16) = w2;
;                 }
.LBB0_751:
	v_mov_b64_e32 v[44:45], s[16:17]
	v_mad_i64_i32 v[42:43], s[38:39], v42, s45, v[44:45]
	v_lshl_add_u64 v[42:43], v[42:43], 0, v[0:1]
	v_lshl_add_u64 v[42:43], s[36:37], 1, v[42:43]
	v_cvt_pk_bf16_f32 v164, v38, v39
	v_cvt_pk_bf16_f32 v165, v40, v41
	v_cvt_pk_bf16_f32 v166, v34, v35
	v_cvt_pk_bf16_f32 v167, v36, v37
	v_add_co_u32_e32 v36, vcc, 0x1000, v42
	v_lshl_add_u64 v[44:45], v[42:43], 0, s[84:85]
	s_nop 0
	v_addc_co_u32_e32 v37, vcc, 0, v43, vcc
	v_lshl_add_u64 v[170:171], v[36:37], 0, v[168:169]
	s_nop 1
	v_permlane16_swap_b32_e32 v164, v166
	v_permlane16_swap_b32_e32 v165, v167
	flat_store_dwordx4 v[170:171], v[164:167]
	s_and_b64 vcc, exec, s[6:7]
	v_add_u32_e32 v34, 0x80, v74
	s_cbranch_vccnz .LBB0_753
	v_mul_hi_i32 v35, v34, s33
	v_lshrrev_b32_e32 v36, 31, v35
	v_ashrrev_i32_e32 v35, 12, v35
	v_add_u32_e32 v35, v35, v36
	v_mul_i32_i24_e32 v35, 0x2080, v35
	v_sub_u32_e32 v36, v34, v35
	v_ashrrev_i32_e32 v37, 31, v36
	v_lshlrev_b64 v[36:37], 7, v[36:37]
	v_lshl_add_u64 v[36:37], s[24:25], 0, v[36:37]
	v_mov_b32_e32 v67, v1
	v_lshl_add_u64 v[40:41], v[36:37], 0, v[66:67]
	flat_load_dwordx4 v[36:39], v[40:41] offset:64
	s_nop 0
	flat_load_dwordx4 v[40:43], v[40:41]
	s_waitcnt vmcnt(0) lgkmcnt(0)
	v_pk_mul_f32 v[44:45], v[28:29], v[38:39]
	v_pk_mul_f32 v[46:47], v[26:27], v[36:37]
	v_pk_mul_f32 v[38:39], v[32:33], v[38:39]
	v_pk_mul_f32 v[36:37], v[30:31], v[36:37]
	v_pk_fma_f32 v[32:33], v[32:33], v[42:43], v[44:45] neg_lo:[0,0,1] neg_hi:[0,0,1]
	v_pk_fma_f32 v[30:31], v[30:31], v[40:41], v[46:47] neg_lo:[0,0,1] neg_hi:[0,0,1]
	v_pk_fma_f32 v[28:29], v[28:29], v[42:43], v[38:39]
	v_pk_fma_f32 v[26:27], v[26:27], v[40:41], v[36:37]
.LBB0_753:
	v_mov_b64_e32 v[36:37], s[16:17]
	v_mad_i64_i32 v[34:35], s[38:39], v34, s45, v[36:37]
	v_lshl_add_u64 v[34:35], v[34:35], 0, v[0:1]
	v_lshl_add_u64 v[34:35], s[36:37], 1, v[34:35]
	v_cvt_pk_bf16_f32 v160, v30, v31
	v_cvt_pk_bf16_f32 v161, v32, v33
	v_cvt_pk_bf16_f32 v162, v26, v27
	v_cvt_pk_bf16_f32 v163, v28, v29
	v_add_co_u32_e32 v28, vcc, 0x1000, v34
	v_lshl_add_u64 v[36:37], v[34:35], 0, s[84:85]
	s_nop 0
	v_addc_co_u32_e32 v29, vcc, 0, v35, vcc
	v_lshl_add_u64 v[170:171], v[28:29], 0, v[168:169]
	s_nop 1
	v_permlane16_swap_b32_e32 v160, v162
	v_permlane16_swap_b32_e32 v161, v163
	flat_store_dwordx4 v[170:171], v[160:163]
	s_and_b64 vcc, exec, s[6:7]
	v_add_u32_e32 v26, 0x90, v74
	s_cbranch_vccnz .LBB0_755
	v_mul_hi_i32 v27, v26, s33
	v_lshrrev_b32_e32 v28, 31, v27
	v_ashrrev_i32_e32 v27, 12, v27
	v_add_u32_e32 v27, v27, v28
	v_mul_i32_i24_e32 v27, 0x2080, v27
	v_sub_u32_e32 v28, v26, v27
	v_ashrrev_i32_e32 v29, 31, v28
	v_lshlrev_b64 v[28:29], 7, v[28:29]
	v_lshl_add_u64 v[28:29], s[24:25], 0, v[28:29]
	v_mov_b32_e32 v67, v1
	v_lshl_add_u64 v[32:33], v[28:29], 0, v[66:67]
	flat_load_dwordx4 v[28:31], v[32:33] offset:64
	s_nop 0
	flat_load_dwordx4 v[32:35], v[32:33]
	s_waitcnt vmcnt(0) lgkmcnt(0)
	v_pk_mul_f32 v[36:37], v[20:21], v[30:31]
	v_pk_mul_f32 v[38:39], v[18:19], v[28:29]
	v_pk_mul_f32 v[30:31], v[24:25], v[30:31]
	v_pk_mul_f32 v[28:29], v[22:23], v[28:29]
	v_pk_fma_f32 v[24:25], v[24:25], v[34:35], v[36:37] neg_lo:[0,0,1] neg_hi:[0,0,1]
	v_pk_fma_f32 v[22:23], v[22:23], v[32:33], v[38:39] neg_lo:[0,0,1] neg_hi:[0,0,1]
	v_pk_fma_f32 v[20:21], v[20:21], v[34:35], v[30:31]
	v_pk_fma_f32 v[18:19], v[18:19], v[32:33], v[28:29]
; __device__ __forceinline__ unsigned cvt_pk_bf16(float lo, float hi) { unsigned r; asm volatile("v_cvt_pk_bf16_f32 %0, %1, %2" : "=v"(r) : "v"(lo), "v"(hi)); return r; }
;     __device__ __forceinline__ void operator()(const f32x4 (&acc)[2][2][4][2], const Unit& u, int wr, int wc, int fr_in, int fq_in) const {
;     ...
;         for (int bj = 0; bj < 2; ++bj) {
;             const int cg0 = u.pn * BM + bj * HALF + wc * 32;
;             if (cg0 >= 384) continue;
;             const bool isrope = ((cg0 >> 5) % 3) == 2;
; #pragma unroll
;             for (int ai = 0; ai < 2; ++ai)
; #pragma unroll
;                 for (int m = 0; m < 4; ++m) {
;                     const int r = row0 + ai * HALF + m * 16;
;                     f32x4 x1 = acc[ai][bj][m][0] * qs, x2 = acc[ai][bj][m][1] * qs;
;                     if (isrope) {
;                         const int s = r % LP;
;                         const f32x4 cs = *(const f32x4*)(rope + (size_t)s * 32 + 4 * fq), sn = *(const f32x4*)(rope + (size_t)s * 32 + 16 + 4 * fq);
;                         const f32x4 o1 = x1 * cs - x2 * sn, o2 = x2 * cs + x1 * sn; x1 = o1; x2 = o2;
;                     }
;                     bf16_t* p = U + (size_t)r * DIN + 2048 + cg0 + 4 * fq;
;                     u32x2 w1, w2; w1.x = cvt_pk_bf16(x1[0], x1[1]); w1.y = cvt_pk_bf16(x1[2], x1[3]); w2.x = cvt_pk_bf16(x2[0], x2[1]); w2.y = cvt_pk_bf16(x2[2], x2[3]);
;                     *(u32x2*)p = w1; *(u32x2*)(p + 16) = w2;
;                 }
.LBB0_755:
	v_mov_b64_e32 v[28:29], s[16:17]
	v_mad_i64_i32 v[26:27], s[38:39], v26, s45, v[28:29]
	v_lshl_add_u64 v[26:27], v[26:27], 0, v[0:1]
	v_lshl_add_u64 v[26:27], s[36:37], 1, v[26:27]
	v_cvt_pk_bf16_f32 v164, v22, v23
	v_cvt_pk_bf16_f32 v165, v24, v25
	v_cvt_pk_bf16_f32 v166, v18, v19
	v_cvt_pk_bf16_f32 v167, v20, v21
	v_add_co_u32_e32 v20, vcc, 0x1000, v26
	v_lshl_add_u64 v[28:29], v[26:27], 0, s[84:85]
	s_nop 0
	v_addc_co_u32_e32 v21, vcc, 0, v27, vcc
	v_lshl_add_u64 v[170:171], v[20:21], 0, v[168:169]
	s_nop 1
	v_permlane16_swap_b32_e32 v164, v166
	v_permlane16_swap_b32_e32 v165, v167
	flat_store_dwordx4 v[170:171], v[164:167]
	s_and_b64 vcc, exec, s[6:7]
	v_add_u32_e32 v18, 0xa0, v74
	s_cbranch_vccnz .LBB0_757
	v_mul_hi_i32 v19, v18, s33
	v_lshrrev_b32_e32 v20, 31, v19
	v_ashrrev_i32_e32 v19, 12, v19
	v_add_u32_e32 v19, v19, v20
	v_mul_i32_i24_e32 v19, 0x2080, v19
	v_sub_u32_e32 v20, v18, v19
	v_ashrrev_i32_e32 v21, 31, v20
	v_lshlrev_b64 v[20:21], 7, v[20:21]
	v_lshl_add_u64 v[20:21], s[24:25], 0, v[20:21]
	v_mov_b32_e32 v67, v1
	v_lshl_add_u64 v[24:25], v[20:21], 0, v[66:67]
	flat_load_dwordx4 v[20:23], v[24:25] offset:64
	s_nop 0
	flat_load_dwordx4 v[24:27], v[24:25]
	s_waitcnt vmcnt(0) lgkmcnt(0)
	v_pk_mul_f32 v[28:29], v[12:13], v[22:23]
	v_pk_mul_f32 v[30:31], v[10:11], v[20:21]
	v_pk_mul_f32 v[22:23], v[16:17], v[22:23]
	v_pk_mul_f32 v[20:21], v[14:15], v[20:21]
	v_pk_fma_f32 v[16:17], v[16:17], v[26:27], v[28:29] neg_lo:[0,0,1] neg_hi:[0,0,1]
	v_pk_fma_f32 v[14:15], v[14:15], v[24:25], v[30:31] neg_lo:[0,0,1] neg_hi:[0,0,1]
	v_pk_fma_f32 v[12:13], v[12:13], v[26:27], v[22:23]
	v_pk_fma_f32 v[10:11], v[10:11], v[24:25], v[20:21]
.LBB0_757:
	v_mov_b64_e32 v[20:21], s[16:17]
	v_mad_i64_i32 v[18:19], s[38:39], v18, s45, v[20:21]
	v_lshl_add_u64 v[18:19], v[18:19], 0, v[0:1]
	v_lshl_add_u64 v[18:19], s[36:37], 1, v[18:19]
	v_cvt_pk_bf16_f32 v160, v14, v15
	v_cvt_pk_bf16_f32 v161, v16, v17
	v_cvt_pk_bf16_f32 v162, v10, v11
	v_cvt_pk_bf16_f32 v163, v12, v13
	v_add_co_u32_e32 v12, vcc, 0x1000, v18
	v_lshl_add_u64 v[20:21], v[18:19], 0, s[84:85]
	s_nop 0
	v_addc_co_u32_e32 v13, vcc, 0, v19, vcc
	v_lshl_add_u64 v[170:171], v[12:13], 0, v[168:169]
	s_nop 1
	v_permlane16_swap_b32_e32 v160, v162
	v_permlane16_swap_b32_e32 v161, v163
	flat_store_dwordx4 v[170:171], v[160:163]
	s_and_b64 vcc, exec, s[6:7]
	v_add_u32_e32 v10, 0xb0, v74
	s_cbranch_vccnz .LBB0_759
	v_mul_hi_i32 v11, v10, s33
	v_lshrrev_b32_e32 v12, 31, v11
	v_ashrrev_i32_e32 v11, 12, v11
	v_add_u32_e32 v11, v11, v12
	v_mul_i32_i24_e32 v11, 0x2080, v11
	v_sub_u32_e32 v12, v10, v11
	v_ashrrev_i32_e32 v13, 31, v12
	v_lshlrev_b64 v[12:13], 7, v[12:13]
	v_lshl_add_u64 v[12:13], s[24:25], 0, v[12:13]
	v_mov_b32_e32 v67, v1
	v_lshl_add_u64 v[16:17], v[12:13], 0, v[66:67]
	flat_load_dwordx4 v[12:15], v[16:17] offset:64
	s_nop 0
	flat_load_dwordx4 v[16:19], v[16:17]
	s_waitcnt vmcnt(0) lgkmcnt(0)
	v_pk_mul_f32 v[20:21], v[4:5], v[14:15]
	v_pk_mul_f32 v[22:23], v[2:3], v[12:13]
	v_pk_mul_f32 v[14:15], v[8:9], v[14:15]
	v_pk_mul_f32 v[12:13], v[6:7], v[12:13]
	v_pk_fma_f32 v[8:9], v[8:9], v[18:19], v[20:21] neg_lo:[0,0,1] neg_hi:[0,0,1]
	v_pk_fma_f32 v[6:7], v[6:7], v[16:17], v[22:23] neg_lo:[0,0,1] neg_hi:[0,0,1]
	v_pk_fma_f32 v[4:5], v[4:5], v[18:19], v[14:15]
	v_pk_fma_f32 v[2:3], v[2:3], v[16:17], v[12:13]
.LBB0_759:
	v_mov_b64_e32 v[12:13], s[16:17]
	v_mad_i64_i32 v[10:11], s[6:7], v10, s45, v[12:13]
	v_lshl_add_u64 v[10:11], v[10:11], 0, v[0:1]
	v_lshl_add_u64 v[10:11], s[36:37], 1, v[10:11]
	v_cvt_pk_bf16_f32 v164, v6, v7
	v_cvt_pk_bf16_f32 v165, v8, v9
	v_cvt_pk_bf16_f32 v166, v2, v3
	v_cvt_pk_bf16_f32 v167, v4, v5
	v_add_co_u32_e32 v4, vcc, 0x1000, v10
	v_lshl_add_u64 v[12:13], v[10:11], 0, s[84:85]
	s_nop 0
	v_addc_co_u32_e32 v5, vcc, 0, v11, vcc
	v_lshl_add_u64 v[170:171], v[4:5], 0, v[168:169]
	s_nop 1
	v_permlane16_swap_b32_e32 v164, v166
	v_permlane16_swap_b32_e32 v165, v167
	flat_store_dwordx4 v[170:171], v[164:167]
	s_and_b64 vcc, exec, s[4:5]
	s_mov_b64 s[4:5], -1
	s_cbranch_vccnz .LBB0_706
